# P9 epilogue: same rstd restructure as P7 (quarter loads + bpermute gathers, per-row reductions removed)
# speedup vs baseline: 1.0211x; 1.0006x over previous
.LBB0_1657:
	v_and_b32_e32 v232, 48, v146
	v_mul_u32_u24_e32 v232, 3, v232
	v_sub_u32_e32 v232, 0, v232
	v_ashrrev_i32_e32 v233, 31, v232
	v_lshl_add_u32 v140, s26, 8, v144
	v_ashrrev_i32_e32 v141, 31, v140
	v_mbcnt_lo_u32_b32 v188, -1, 0
	v_mbcnt_hi_u32_b32 v188, -1, v188
	v_lshlrev_b64 v[236:237], 6, v[140:141]
	v_lshl_add_u64 v[236:237], s[6:7], 0, v[236:237]
	v_and_b32_e32 v238, 48, v188
	v_mov_b32_e32 v239, 0
	s_mov_b64 s[98:99], 0x2000
	v_lshl_add_u64 v[236:237], v[236:237], 0, v[238:239]
	v_lshl_add_u64 v[238:239], v[236:237], 0, s[98:99]
	global_load_dwordx4 v[152:155], v[236:237], off
	global_load_dwordx4 v[156:159], v[236:237], off offset:1024
	global_load_dwordx4 v[160:163], v[236:237], off offset:2048
	global_load_dwordx4 v[164:167], v[236:237], off offset:3072
	global_load_dwordx4 v[192:195], v[238:239], off
	global_load_dwordx4 v[196:199], v[238:239], off offset:1024
	global_load_dwordx4 v[200:203], v[238:239], off offset:2048
	global_load_dwordx4 v[204:207], v[238:239], off offset:3072
	v_and_b32_e32 v189, 15, v188
	v_lshlrev_b32_e32 v189, 2, v189
	v_add_u32_e32 v190, 64, v189
	v_add_u32_e32 v191, 128, v189
	v_add_u32_e32 v188, 192, v189
	v_lshlrev_b64 v[138:139], 6, v[140:141]
	v_lshl_add_u64 v[138:139], s[6:7], 0, v[138:139]
	v_lshl_or_b32 v142, s24, 8, v146
	v_ashrrev_i32_e32 v143, 31, v142
	v_lshlrev_b64 v[168:169], 11, v[140:141]
	v_lshlrev_b64 v[138:139], 1, v[142:143]
	v_lshl_add_u64 v[170:171], s[8:9], 0, v[168:169]
	v_lshl_add_u64 v[172:173], s[0:1], 0, v[168:169]
	v_lshl_add_u64 v[176:177], v[170:171], 0, v[138:139]
	v_lshl_add_u64 v[180:181], v[172:173], 0, v[138:139]
	global_load_dwordx4 v[168:171], v[176:177], off
	global_load_dwordx4 v[172:175], v[180:181], off
	s_nop 0
	global_load_dwordx4 v[176:179], v[176:177], off offset:16
	s_nop 0
	global_load_dwordx4 v[180:183], v[180:181], off offset:16
	s_cmp_eq_u32 s25, s47
	s_mov_b64 s[24:25], -1
	s_waitcnt vmcnt(0)
	v_add_f32_e32 v152, v152, v153
	v_add_f32_e32 v154, v154, v155
	v_add_f32_e32 v156, v156, v157
	v_add_f32_e32 v158, v158, v159
	v_add_f32_e32 v160, v160, v161
	v_add_f32_e32 v162, v162, v163
	v_add_f32_e32 v164, v164, v165
	v_add_f32_e32 v166, v166, v167
	v_add_f32_e32 v192, v192, v193
	v_add_f32_e32 v194, v194, v195
	v_add_f32_e32 v196, v196, v197
	v_add_f32_e32 v198, v198, v199
	v_add_f32_e32 v200, v200, v201
	v_add_f32_e32 v202, v202, v203
	v_add_f32_e32 v204, v204, v205
	v_add_f32_e32 v206, v206, v207
	v_add_f32_e32 v152, v152, v154
	v_add_f32_e32 v156, v156, v158
	v_add_f32_e32 v160, v160, v162
	v_add_f32_e32 v164, v164, v166
	v_add_f32_e32 v192, v192, v194
	v_add_f32_e32 v196, v196, v198
	v_add_f32_e32 v200, v200, v202
	v_add_f32_e32 v204, v204, v206
	ds_bpermute_b32 v153, v189, v152
	ds_bpermute_b32 v157, v189, v156
	ds_bpermute_b32 v161, v189, v160
	ds_bpermute_b32 v165, v189, v164
	ds_bpermute_b32 v193, v189, v192
	ds_bpermute_b32 v197, v189, v196
	ds_bpermute_b32 v201, v189, v200
	ds_bpermute_b32 v205, v189, v204
	s_waitcnt lgkmcnt(0)
	ds_bpermute_b32 v154, v190, v152
	ds_bpermute_b32 v158, v190, v156
	ds_bpermute_b32 v162, v190, v160
	ds_bpermute_b32 v166, v190, v164
	ds_bpermute_b32 v194, v190, v192
	ds_bpermute_b32 v198, v190, v196
	ds_bpermute_b32 v202, v190, v200
	ds_bpermute_b32 v206, v190, v204
	s_waitcnt lgkmcnt(0)
	v_add_f32_e32 v153, v153, v154
	v_add_f32_e32 v157, v157, v158
	v_add_f32_e32 v161, v161, v162
	v_add_f32_e32 v165, v165, v166
	v_add_f32_e32 v193, v193, v194
	v_add_f32_e32 v197, v197, v198
	v_add_f32_e32 v201, v201, v202
	v_add_f32_e32 v205, v205, v206
	ds_bpermute_b32 v154, v191, v152
	ds_bpermute_b32 v158, v191, v156
	ds_bpermute_b32 v162, v191, v160
	ds_bpermute_b32 v166, v191, v164
	ds_bpermute_b32 v194, v191, v192
	ds_bpermute_b32 v198, v191, v196
	ds_bpermute_b32 v202, v191, v200
	ds_bpermute_b32 v206, v191, v204
	s_waitcnt lgkmcnt(0)
	v_add_f32_e32 v153, v153, v154
	v_add_f32_e32 v157, v157, v158
	v_add_f32_e32 v161, v161, v162
	v_add_f32_e32 v165, v165, v166
	v_add_f32_e32 v193, v193, v194
	v_add_f32_e32 v197, v197, v198
	v_add_f32_e32 v201, v201, v202
	v_add_f32_e32 v205, v205, v206
	ds_bpermute_b32 v154, v188, v152
	ds_bpermute_b32 v158, v188, v156
	ds_bpermute_b32 v162, v188, v160
	ds_bpermute_b32 v166, v188, v164
	ds_bpermute_b32 v194, v188, v192
	ds_bpermute_b32 v198, v188, v196
	ds_bpermute_b32 v202, v188, v200
	ds_bpermute_b32 v206, v188, v204
	s_waitcnt lgkmcnt(0)
	v_add_f32_e32 v208, v153, v154
	v_add_f32_e32 v209, v157, v158
	v_add_f32_e32 v210, v161, v162
	v_add_f32_e32 v211, v165, v166
	v_add_f32_e32 v212, v193, v194
	v_add_f32_e32 v213, v197, v198
	v_add_f32_e32 v214, v201, v202
	v_add_f32_e32 v215, v205, v206
	v_lshlrev_b32_e32 v158, 16, v168
	v_and_b32_e32 v159, 0xffff0000, v168
	s_nop 1
	v_mov_b32_e32 v151, v208
	v_fmamk_f32 v151, v151, 0x3a800000, v150
	v_mul_f32_e32 v152, 0x4b800000, v151
	v_cmp_gt_f32_e32 vcc, s51, v151
	v_and_b32_e32 v153, 0xffff0000, v176
	v_lshlrev_b32_e32 v162, 16, v172
	v_cndmask_b32_e32 v151, v151, v152, vcc
	v_rsq_f32_e32 v151, v151
	v_lshlrev_b32_e32 v152, 16, v176
	v_and_b32_e32 v163, 0xffff0000, v172
	v_lshlrev_b32_e32 v164, 16, v169
	v_mul_f32_e32 v155, 0x45800000, v151
	v_cndmask_b32_e32 v151, v151, v155, vcc
	v_mul_f32_e32 v151, 0xbfb8aa3b, v151
	v_mul_f32_e32 v127, v127, v151
	v_mul_f32_e32 v117, v117, v151
	v_mul_f32_e32 v112, v112, v151
	v_mul_f32_e32 v124, v124, v151
	v_mul_f32_e32 v121, v121, v151
	v_mul_f32_e32 v122, v122, v151
	v_exp_f32_e32 v127, v127
	v_exp_f32_e32 v117, v117
	v_exp_f32_e32 v112, v112
	v_mul_f32_e32 v113, v113, v151
	v_mul_f32_e32 v120, v120, v151
	v_mul_f32_e32 v123, v123, v151
	v_exp_f32_e32 v124, v124
	v_exp_f32_e32 v121, v121
	v_exp_f32_e32 v122, v122
	v_exp_f32_e32 v113, v113
	v_exp_f32_e32 v120, v120
	v_exp_f32_e32 v123, v123
	v_add_f32_e32 v127, 1.0, v127
	v_add_f32_e32 v176, 1.0, v117
	v_add_f32_e32 v112, 1.0, v112
	v_mul_f32_e32 v125, v125, v151
	v_mul_f32_e32 v126, v126, v151
	v_add_f32_e32 v124, 1.0, v124
	v_add_f32_e32 v156, 1.0, v121
	v_add_f32_e32 v157, 1.0, v122
	v_rcp_f32_e32 v117, v127
	v_rcp_f32_e32 v127, v176
	v_rcp_f32_e32 v176, v112
	v_add_f32_e32 v112, 1.0, v113
	v_mul_f32_e32 v116, v116, v151
	v_exp_f32_e32 v125, v125
	v_exp_f32_e32 v126, v126
	v_add_f32_e32 v155, 1.0, v120
	v_add_f32_e32 v160, 1.0, v123
	v_rcp_f32_e32 v120, v124
	v_rcp_f32_e32 v123, v156
	v_rcp_f32_e32 v124, v157
	v_lshlrev_b32_e32 v156, 16, v177
	v_and_b32_e32 v157, 0xffff0000, v177
	v_rcp_f32_e32 v177, v112
	v_mul_f32_e32 v112, v114, v151
	v_mul_f32_e32 v118, v118, v151
	v_exp_f32_e32 v116, v116
	v_mul_f32_e32 v119, v119, v151
	v_exp_f32_e32 v112, v112
	v_mul_f32_e32 v113, v115, v151
	v_exp_f32_e32 v118, v118
	v_exp_f32_e32 v119, v119
	v_exp_f32_e32 v113, v113
	v_add_f32_e32 v125, 1.0, v125
	v_add_f32_e32 v126, 1.0, v126
	v_add_f32_e32 v161, 1.0, v116
	v_rcp_f32_e32 v121, v125
	v_rcp_f32_e32 v116, v126
	v_add_f32_e32 v112, 1.0, v112
	v_rcp_f32_e32 v122, v155
	v_rcp_f32_e32 v125, v160
	v_add_f32_e32 v118, 1.0, v118
	v_add_f32_e32 v119, 1.0, v119
	v_rcp_f32_e32 v186, v112
	v_add_f32_e32 v112, 1.0, v113
	v_rcp_f32_e32 v126, v161
	v_rcp_f32_e32 v118, v118
	v_rcp_f32_e32 v119, v119
	v_rcp_f32_e32 v187, v112
	v_lshlrev_b64 v[112:113], 12, v[140:141]
	v_and_b32_e32 v165, 0xffff0000, v169
	v_lshlrev_b32_e32 v166, 16, v173
	v_and_b32_e32 v167, 0xffff0000, v173
	v_lshl_add_u64 v[114:115], s[84:85], 0, v[112:113]
	v_lshlrev_b64 v[112:113], 2, v[142:143]
	v_lshlrev_b32_e32 v168, 16, v170
	v_and_b32_e32 v169, 0xffff0000, v170
	v_lshlrev_b32_e32 v172, 16, v174
	v_and_b32_e32 v173, 0xffff0000, v174
	v_lshlrev_b32_e32 v170, 16, v171
	v_and_b32_e32 v171, 0xffff0000, v171
	v_lshlrev_b32_e32 v174, 16, v175
	v_and_b32_e32 v175, 0xffff0000, v175
	v_lshl_add_u64 v[142:143], v[114:115], 0, v[112:113]
	v_pk_fma_f32 v[218:219], v[116:117], v[164:165], v[166:167]
	v_pk_fma_f32 v[216:217], v[120:121], v[158:159], v[162:163]
	v_lshlrev_b32_e32 v154, 16, v180
	v_and_b32_e32 v155, 0xffff0000, v180
	v_lshlrev_b32_e32 v160, 16, v181
	v_and_b32_e32 v161, 0xffff0000, v181
	v_lshlrev_b32_e32 v180, 16, v178
	v_and_b32_e32 v181, 0xffff0000, v178
	v_pk_fma_f32 v[222:223], v[124:125], v[170:171], v[174:175]
	v_pk_fma_f32 v[220:221], v[122:123], v[168:169], v[172:173]
	v_lshlrev_b32_e32 v184, 16, v182
	v_and_b32_e32 v185, 0xffff0000, v182
	v_lshlrev_b32_e32 v178, 16, v179
	v_and_b32_e32 v179, 0xffff0000, v179
	v_lshlrev_b32_e32 v182, 16, v183
	v_and_b32_e32 v183, 0xffff0000, v183
	s_nop 1
	v_pk_fma_f32 v[226:227], v[118:119], v[156:157], v[160:161]
	v_pk_fma_f32 v[224:225], v[126:127], v[152:153], v[154:155]
	v_or_b32_e32 v126, 16, v140
	v_ashrrev_i32_e32 v127, 31, v126
	s_nop 0
	v_pk_fma_f32 v[230:231], v[186:187], v[178:179], v[182:183]
	v_pk_fma_f32 v[228:229], v[176:177], v[180:181], v[184:185]
	s_nop 1
	v_permlane16_swap_b32_e32 v216, v220
	v_permlane16_swap_b32_e32 v217, v221
	v_permlane16_swap_b32_e32 v218, v222
	v_permlane16_swap_b32_e32 v219, v223
	v_permlane16_swap_b32_e32 v224, v228
	v_permlane16_swap_b32_e32 v225, v229
	v_permlane16_swap_b32_e32 v226, v230
	v_permlane16_swap_b32_e32 v227, v231
	v_permlane32_swap_b32_e32 v216, v224
	v_permlane32_swap_b32_e32 v217, v225
	v_permlane32_swap_b32_e32 v218, v226
	v_permlane32_swap_b32_e32 v219, v227
	v_permlane32_swap_b32_e32 v220, v228
	v_permlane32_swap_b32_e32 v221, v229
	v_permlane32_swap_b32_e32 v222, v230
	v_permlane32_swap_b32_e32 v223, v231
	v_lshl_add_u64 v[234:235], v[142:143], 0, v[232:233]
	global_store_dwordx4 v[234:235], v[216:219], off
	global_store_dwordx4 v[234:235], v[220:223], off offset:64
	global_store_dwordx4 v[234:235], v[224:227], off offset:128
	global_store_dwordx4 v[234:235], v[228:231], off offset:192
	s_nop 1
	v_lshlrev_b64 v[114:115], 6, v[126:127]
	v_lshl_add_u64 v[142:143], s[6:7], 0, v[114:115]
	v_lshlrev_b64 v[142:143], 11, v[126:127]
	v_lshl_add_u64 v[156:157], s[8:9], 0, v[142:143]
	v_lshl_add_u64 v[142:143], s[0:1], 0, v[142:143]
	v_lshl_add_u64 v[164:165], v[156:157], 0, v[138:139]
	v_lshl_add_u64 v[142:143], v[142:143], 0, v[138:139]
	global_load_dwordx4 v[156:159], v[164:165], off
	global_load_dwordx4 v[160:163], v[142:143], off
	s_nop 0
	global_load_dwordx4 v[164:167], v[164:165], off offset:16
	s_nop 0
	global_load_dwordx4 v[168:171], v[142:143], off offset:16
	s_waitcnt vmcnt(7)
	s_waitcnt vmcnt(6)
	s_waitcnt vmcnt(5)
	s_waitcnt vmcnt(4)
	s_waitcnt vmcnt(2)
	v_lshlrev_b32_e32 v124, 16, v162
	v_and_b32_e32 v125, 0xffff0000, v162
	s_nop 1
	v_mov_b32_e32 v114, v209
	v_fmamk_f32 v114, v114, 0x3a800000, v150
	v_mul_f32_e32 v115, 0x4b800000, v114
	v_cmp_gt_f32_e32 vcc, s51, v114
	v_lshlrev_b32_e32 v152, 16, v163
	v_and_b32_e32 v153, 0xffff0000, v163
	v_cndmask_b32_e32 v114, v114, v115, vcc
	v_rsq_f32_e32 v116, v114
	v_lshlrev_b32_e32 v114, 16, v156
	v_and_b32_e32 v115, 0xffff0000, v156
	v_lshlrev_b32_e32 v118, 16, v157
	v_mul_f32_e32 v117, 0x45800000, v116
	v_cndmask_b32_e32 v116, v116, v117, vcc
	v_mul_f32_e32 v141, 0xbfb8aa3b, v116
	v_mul_f32_e32 v109, v109, v141
	v_mul_f32_e32 v96, v96, v141
	v_exp_f32_e32 v109, v109
	v_exp_f32_e32 v96, v96
	v_mul_f32_e32 v97, v97, v141
	v_exp_f32_e32 v97, v97
	v_add_f32_e32 v109, 1.0, v109
	v_add_f32_e32 v96, 1.0, v96
	v_mul_f32_e32 v108, v108, v141
	v_mul_f32_e32 v110, v110, v141
	v_rcp_f32_e32 v117, v109
	v_mul_f32_e32 v109, v111, v141
	v_rcp_f32_e32 v162, v96
	v_add_f32_e32 v96, 1.0, v97
	v_exp_f32_e32 v116, v108
	v_exp_f32_e32 v110, v110
	v_exp_f32_e32 v111, v109
	v_mul_f32_e32 v104, v104, v141
	v_mul_f32_e32 v105, v105, v141
	v_mul_f32_e32 v106, v106, v141
	v_mul_f32_e32 v107, v107, v141
	v_rcp_f32_e32 v163, v96
	v_mul_f32_e32 v96, v98, v141
	v_exp_f32_e32 v104, v104
	v_exp_f32_e32 v105, v105
	v_exp_f32_e32 v106, v106
	v_exp_f32_e32 v107, v107
	v_mul_f32_e32 v100, v100, v141
	v_mul_f32_e32 v101, v101, v141
	v_mul_f32_e32 v102, v102, v141
	v_mul_f32_e32 v103, v103, v141
	v_exp_f32_e32 v96, v96
	v_mul_f32_e32 v97, v99, v141
	v_exp_f32_e32 v100, v100
	v_exp_f32_e32 v101, v101
	v_exp_f32_e32 v102, v102
	v_exp_f32_e32 v103, v103
	v_exp_f32_e32 v97, v97
	v_add_f32_e32 v116, 1.0, v116
	v_add_f32_e32 v110, 1.0, v110
	v_add_f32_e32 v111, 1.0, v111
	v_rcp_f32_e32 v116, v116
	v_rcp_f32_e32 v110, v110
	v_rcp_f32_e32 v111, v111
	v_add_f32_e32 v104, 1.0, v104
	v_add_f32_e32 v105, 1.0, v105
	v_add_f32_e32 v106, 1.0, v106
	v_add_f32_e32 v107, 1.0, v107
	v_add_f32_e32 v96, 1.0, v96
	v_rcp_f32_e32 v104, v104
	v_rcp_f32_e32 v105, v105
	v_rcp_f32_e32 v106, v106
	v_rcp_f32_e32 v107, v107
	v_add_f32_e32 v100, 1.0, v100
	v_add_f32_e32 v101, 1.0, v101
	v_add_f32_e32 v102, 1.0, v102
	v_add_f32_e32 v103, 1.0, v103
	v_rcp_f32_e32 v172, v96
	v_add_f32_e32 v96, 1.0, v97
	v_rcp_f32_e32 v100, v100
	v_rcp_f32_e32 v101, v101
	v_rcp_f32_e32 v102, v102
	v_rcp_f32_e32 v103, v103
	v_rcp_f32_e32 v173, v96
	v_lshlrev_b64 v[96:97], 12, v[126:127]
	v_lshlrev_b32_e32 v108, 16, v160
	v_and_b32_e32 v109, 0xffff0000, v160
	v_and_b32_e32 v119, 0xffff0000, v157
	v_lshlrev_b32_e32 v120, 16, v161
	v_and_b32_e32 v121, 0xffff0000, v161
	v_lshl_add_u64 v[96:97], s[84:85], 0, v[96:97]
	v_lshlrev_b32_e32 v122, 16, v158
	v_and_b32_e32 v123, 0xffff0000, v158
	v_lshlrev_b32_e32 v142, 16, v159
	v_and_b32_e32 v143, 0xffff0000, v159
	v_lshl_add_u64 v[126:127], v[96:97], 0, v[112:113]
	v_pk_fma_f32 v[218:219], v[110:111], v[118:119], v[120:121]
	v_pk_fma_f32 v[216:217], v[116:117], v[114:115], v[108:109]
	s_waitcnt vmcnt(1)
	v_lshlrev_b32_e32 v154, 16, v164
	v_and_b32_e32 v155, 0xffff0000, v164
	s_waitcnt vmcnt(0)
	v_lshlrev_b32_e32 v156, 16, v168
	v_and_b32_e32 v157, 0xffff0000, v168
	v_lshlrev_b32_e32 v158, 16, v165
	v_and_b32_e32 v159, 0xffff0000, v165
	v_lshlrev_b32_e32 v160, 16, v169
	v_and_b32_e32 v161, 0xffff0000, v169
	v_lshlrev_b32_e32 v164, 16, v166
	v_and_b32_e32 v165, 0xffff0000, v166
	v_pk_fma_f32 v[222:223], v[106:107], v[142:143], v[152:153]
	v_pk_fma_f32 v[220:221], v[104:105], v[122:123], v[124:125]
	v_lshlrev_b32_e32 v168, 16, v170
	v_and_b32_e32 v169, 0xffff0000, v170
	v_lshlrev_b32_e32 v166, 16, v167
	v_and_b32_e32 v167, 0xffff0000, v167
	v_lshlrev_b32_e32 v170, 16, v171
	v_and_b32_e32 v171, 0xffff0000, v171
	s_nop 1
	v_pk_fma_f32 v[226:227], v[102:103], v[158:159], v[160:161]
	v_pk_fma_f32 v[224:225], v[100:101], v[154:155], v[156:157]
	s_nop 1
	v_pk_fma_f32 v[230:231], v[172:173], v[166:167], v[170:171]
	v_pk_fma_f32 v[228:229], v[162:163], v[164:165], v[168:169]
	s_nop 1
	v_permlane16_swap_b32_e32 v216, v220
	v_permlane16_swap_b32_e32 v217, v221
	v_permlane16_swap_b32_e32 v218, v222
	v_permlane16_swap_b32_e32 v219, v223
	v_permlane16_swap_b32_e32 v224, v228
	v_permlane16_swap_b32_e32 v225, v229
	v_permlane16_swap_b32_e32 v226, v230
	v_permlane16_swap_b32_e32 v227, v231
	v_permlane32_swap_b32_e32 v216, v224
	v_permlane32_swap_b32_e32 v217, v225
	v_permlane32_swap_b32_e32 v218, v226
	v_permlane32_swap_b32_e32 v219, v227
	v_permlane32_swap_b32_e32 v220, v228
	v_permlane32_swap_b32_e32 v221, v229
	v_permlane32_swap_b32_e32 v222, v230
	v_permlane32_swap_b32_e32 v223, v231
	v_lshl_add_u64 v[234:235], v[126:127], 0, v[232:233]
	global_store_dwordx4 v[234:235], v[216:219], off
	global_store_dwordx4 v[234:235], v[220:223], off offset:64
	global_store_dwordx4 v[234:235], v[224:227], off offset:128
	global_store_dwordx4 v[234:235], v[228:231], off offset:192
	v_or_b32_e32 v126, 32, v140
	v_ashrrev_i32_e32 v127, 31, v126
	v_lshlrev_b64 v[96:97], 6, v[126:127]
	v_lshl_add_u64 v[108:109], s[6:7], 0, v[96:97]
	s_nop 0
	v_lshlrev_b64 v[114:115], 11, v[126:127]
	v_lshl_add_u64 v[116:117], s[8:9], 0, v[114:115]
	v_lshl_add_u64 v[122:123], v[116:117], 0, v[138:139]
	v_lshl_add_u64 v[118:119], s[0:1], 0, v[114:115]
	global_load_dwordx4 v[114:117], v[122:123], off
	v_lshl_add_u64 v[142:143], v[118:119], 0, v[138:139]
	global_load_dwordx4 v[118:121], v[142:143], off
	s_nop 0
	global_load_dwordx4 v[122:125], v[122:123], off offset:16
	s_nop 0
	global_load_dwordx4 v[152:155], v[142:143], off offset:16
	s_waitcnt vmcnt(7)
	s_waitcnt vmcnt(6)
	s_waitcnt vmcnt(5)
	s_waitcnt vmcnt(4)
	s_waitcnt vmcnt(3)
	v_lshlrev_b32_e32 v100, 16, v115
	v_and_b32_e32 v101, 0xffff0000, v115
	s_nop 1
	v_mov_b32_e32 v96, v210
	v_fmamk_f32 v96, v96, 0x3a800000, v150
	v_mul_f32_e32 v97, 0x4b800000, v96
	v_cmp_gt_f32_e32 vcc, s51, v96
	s_waitcnt vmcnt(1)
	v_and_b32_e32 v115, 0xffff0000, v122
	v_lshlrev_b32_e32 v98, 16, v118
	v_cndmask_b32_e32 v96, v96, v97, vcc
	v_rsq_f32_e32 v96, v96
	v_and_b32_e32 v99, 0xffff0000, v118
	v_lshlrev_b32_e32 v102, 16, v119
	v_and_b32_e32 v103, 0xffff0000, v119
	v_mul_f32_e32 v97, 0x45800000, v96
	v_cndmask_b32_e32 v96, v96, v97, vcc
	v_mul_f32_e32 v141, 0xbfb8aa3b, v96
	v_mul_f32_e32 v80, v80, v141
	v_exp_f32_e32 v80, v80
	v_mul_f32_e32 v81, v81, v141
	v_exp_f32_e32 v81, v81
	v_mul_f32_e32 v92, v92, v141
	v_add_f32_e32 v80, 1.0, v80
	v_mul_f32_e32 v93, v93, v141
	v_lshlrev_b32_e32 v96, 16, v114
	v_and_b32_e32 v97, 0xffff0000, v114
	v_mul_f32_e32 v94, v94, v141
	v_mul_f32_e32 v95, v95, v141
	v_lshlrev_b32_e32 v114, 16, v122
	v_rcp_f32_e32 v122, v80
	v_add_f32_e32 v80, 1.0, v81
	v_exp_f32_e32 v92, v92
	v_exp_f32_e32 v93, v93
	v_exp_f32_e32 v94, v94
	v_exp_f32_e32 v95, v95
	v_mul_f32_e32 v88, v88, v141
	v_mul_f32_e32 v89, v89, v141
	v_mul_f32_e32 v90, v90, v141
	v_mul_f32_e32 v91, v91, v141
	v_lshlrev_b32_e32 v118, 16, v123
	v_and_b32_e32 v119, 0xffff0000, v123
	v_rcp_f32_e32 v123, v80
	v_mul_f32_e32 v80, v82, v141
	v_exp_f32_e32 v88, v88
	v_exp_f32_e32 v89, v89
	v_exp_f32_e32 v90, v90
	v_exp_f32_e32 v91, v91
	v_mul_f32_e32 v84, v84, v141
	v_mul_f32_e32 v85, v85, v141
	v_mul_f32_e32 v86, v86, v141
	v_mul_f32_e32 v87, v87, v141
	v_exp_f32_e32 v80, v80
	v_mul_f32_e32 v81, v83, v141
	v_exp_f32_e32 v84, v84
	v_exp_f32_e32 v85, v85
	v_exp_f32_e32 v86, v86
	v_exp_f32_e32 v87, v87
	v_exp_f32_e32 v81, v81
	v_add_f32_e32 v92, 1.0, v92
	v_add_f32_e32 v93, 1.0, v93
	v_add_f32_e32 v94, 1.0, v94
	v_add_f32_e32 v95, 1.0, v95
	v_rcp_f32_e32 v92, v92
	v_rcp_f32_e32 v93, v93
	v_rcp_f32_e32 v94, v94
	v_rcp_f32_e32 v95, v95
	v_add_f32_e32 v88, 1.0, v88
	v_add_f32_e32 v89, 1.0, v89
	v_add_f32_e32 v90, 1.0, v90
	v_add_f32_e32 v91, 1.0, v91
	v_add_f32_e32 v80, 1.0, v80
	v_rcp_f32_e32 v88, v88
	v_rcp_f32_e32 v89, v89
	v_rcp_f32_e32 v90, v90
	v_rcp_f32_e32 v91, v91
	v_add_f32_e32 v84, 1.0, v84
	v_add_f32_e32 v85, 1.0, v85
	v_add_f32_e32 v86, 1.0, v86
	v_add_f32_e32 v87, 1.0, v87
	v_rcp_f32_e32 v156, v80
	v_add_f32_e32 v80, 1.0, v81
	v_rcp_f32_e32 v84, v84
	v_rcp_f32_e32 v85, v85
	v_rcp_f32_e32 v86, v86
	v_rcp_f32_e32 v87, v87
	v_rcp_f32_e32 v157, v80
	v_lshlrev_b64 v[80:81], 12, v[126:127]
	v_lshl_add_u64 v[80:81], s[84:85], 0, v[80:81]
	v_lshlrev_b32_e32 v104, 16, v116
	v_and_b32_e32 v105, 0xffff0000, v116
	v_lshlrev_b32_e32 v106, 16, v120
	v_and_b32_e32 v107, 0xffff0000, v120
	v_lshlrev_b32_e32 v108, 16, v117
	v_and_b32_e32 v109, 0xffff0000, v117
	v_lshlrev_b32_e32 v110, 16, v121
	v_and_b32_e32 v111, 0xffff0000, v121
	v_lshl_add_u64 v[126:127], v[80:81], 0, v[112:113]
	v_pk_fma_f32 v[218:219], v[94:95], v[100:101], v[102:103]
	v_pk_fma_f32 v[216:217], v[92:93], v[96:97], v[98:99]
	s_waitcnt vmcnt(0)
	v_lshlrev_b32_e32 v116, 16, v152
	v_and_b32_e32 v117, 0xffff0000, v152
	v_lshlrev_b32_e32 v120, 16, v153
	v_and_b32_e32 v121, 0xffff0000, v153
	v_lshlrev_b32_e32 v142, 16, v124
	v_and_b32_e32 v143, 0xffff0000, v124
	v_pk_fma_f32 v[222:223], v[90:91], v[108:109], v[110:111]
	v_pk_fma_f32 v[220:221], v[88:89], v[104:105], v[106:107]
	v_lshlrev_b32_e32 v152, 16, v154
	v_and_b32_e32 v153, 0xffff0000, v154
	v_lshlrev_b32_e32 v124, 16, v125
	v_and_b32_e32 v125, 0xffff0000, v125
	v_lshlrev_b32_e32 v154, 16, v155
	v_and_b32_e32 v155, 0xffff0000, v155
	s_nop 1
	v_pk_fma_f32 v[226:227], v[86:87], v[118:119], v[120:121]
	v_pk_fma_f32 v[224:225], v[84:85], v[114:115], v[116:117]
	v_or_b32_e32 v114, 48, v140
	v_ashrrev_i32_e32 v115, 31, v114
	s_nop 0
	v_pk_fma_f32 v[230:231], v[156:157], v[124:125], v[154:155]
	v_pk_fma_f32 v[228:229], v[122:123], v[142:143], v[152:153]
	s_nop 1
	v_permlane16_swap_b32_e32 v216, v220
	v_permlane16_swap_b32_e32 v217, v221
	v_permlane16_swap_b32_e32 v218, v222
	v_permlane16_swap_b32_e32 v219, v223
	v_permlane16_swap_b32_e32 v224, v228
	v_permlane16_swap_b32_e32 v225, v229
	v_permlane16_swap_b32_e32 v226, v230
	v_permlane16_swap_b32_e32 v227, v231
	v_permlane32_swap_b32_e32 v216, v224
	v_permlane32_swap_b32_e32 v217, v225
	v_permlane32_swap_b32_e32 v218, v226
	v_permlane32_swap_b32_e32 v219, v227
	v_permlane32_swap_b32_e32 v220, v228
	v_permlane32_swap_b32_e32 v221, v229
	v_permlane32_swap_b32_e32 v222, v230
	v_permlane32_swap_b32_e32 v223, v231
	v_lshl_add_u64 v[234:235], v[126:127], 0, v[232:233]
	global_store_dwordx4 v[234:235], v[216:219], off
	global_store_dwordx4 v[234:235], v[220:223], off offset:64
	global_store_dwordx4 v[234:235], v[224:227], off offset:128
	global_store_dwordx4 v[234:235], v[228:231], off offset:192
	s_nop 1
	v_lshlrev_b64 v[80:81], 6, v[114:115]
	v_lshl_add_u64 v[96:97], s[6:7], 0, v[80:81]
	v_lshlrev_b64 v[96:97], 11, v[114:115]
	v_lshl_add_u64 v[98:99], s[8:9], 0, v[96:97]
	v_lshl_add_u64 v[104:105], v[98:99], 0, v[138:139]
	v_lshl_add_u64 v[100:101], s[0:1], 0, v[96:97]
	global_load_dwordx4 v[96:99], v[104:105], off
	v_lshl_add_u64 v[108:109], v[100:101], 0, v[138:139]
	global_load_dwordx4 v[100:103], v[108:109], off
	s_nop 0
	global_load_dwordx4 v[104:107], v[104:105], off offset:16
	s_nop 0
	global_load_dwordx4 v[108:111], v[108:109], off offset:16
	s_waitcnt vmcnt(7)
	s_waitcnt vmcnt(6)
	s_waitcnt vmcnt(5)
	s_waitcnt vmcnt(4)
	s_waitcnt vmcnt(3)
	v_lshlrev_b32_e32 v84, 16, v97
	v_and_b32_e32 v85, 0xffff0000, v97
	s_nop 1
	v_mov_b32_e32 v80, v211
	v_fmamk_f32 v80, v80, 0x3a800000, v150
	v_mul_f32_e32 v81, 0x4b800000, v80
	v_cmp_gt_f32_e32 vcc, s51, v80
	s_waitcnt vmcnt(1)
	v_and_b32_e32 v97, 0xffff0000, v104
	v_lshlrev_b32_e32 v82, 16, v100
	v_cndmask_b32_e32 v80, v80, v81, vcc
	v_rsq_f32_e32 v80, v80
	v_and_b32_e32 v83, 0xffff0000, v100
	v_lshlrev_b32_e32 v86, 16, v101
	v_and_b32_e32 v87, 0xffff0000, v101
	v_mul_f32_e32 v81, 0x45800000, v80
	v_cndmask_b32_e32 v80, v80, v81, vcc
	v_mul_f32_e32 v117, 0xbfb8aa3b, v80
	v_mul_f32_e32 v64, v64, v117
	v_exp_f32_e32 v64, v64
	v_mul_f32_e32 v65, v65, v117
	v_exp_f32_e32 v65, v65
	v_mul_f32_e32 v76, v76, v117
	v_add_f32_e32 v64, 1.0, v64
	v_mul_f32_e32 v77, v77, v117
	v_lshlrev_b32_e32 v80, 16, v96
	v_and_b32_e32 v81, 0xffff0000, v96
	v_mul_f32_e32 v78, v78, v117
	v_mul_f32_e32 v79, v79, v117
	v_lshlrev_b32_e32 v96, 16, v104
	v_rcp_f32_e32 v104, v64
	v_add_f32_e32 v64, 1.0, v65
	v_exp_f32_e32 v76, v76
	v_exp_f32_e32 v77, v77
	v_exp_f32_e32 v78, v78
	v_exp_f32_e32 v79, v79
	v_mul_f32_e32 v72, v72, v117
	v_mul_f32_e32 v73, v73, v117
	v_mul_f32_e32 v74, v74, v117
	v_mul_f32_e32 v75, v75, v117
	v_lshlrev_b32_e32 v100, 16, v105
	v_and_b32_e32 v101, 0xffff0000, v105
	v_rcp_f32_e32 v105, v64
	v_mul_f32_e32 v64, v66, v117
	v_exp_f32_e32 v72, v72
	v_exp_f32_e32 v73, v73
	v_exp_f32_e32 v74, v74
	v_exp_f32_e32 v75, v75
	v_mul_f32_e32 v68, v68, v117
	v_mul_f32_e32 v69, v69, v117
	v_mul_f32_e32 v70, v70, v117
	v_mul_f32_e32 v71, v71, v117
	v_exp_f32_e32 v64, v64
	v_mul_f32_e32 v65, v67, v117
	v_exp_f32_e32 v68, v68
	v_exp_f32_e32 v69, v69
	v_exp_f32_e32 v70, v70
	v_exp_f32_e32 v71, v71
	v_exp_f32_e32 v65, v65
	v_add_f32_e32 v76, 1.0, v76
	v_add_f32_e32 v77, 1.0, v77
	v_add_f32_e32 v78, 1.0, v78
	v_add_f32_e32 v79, 1.0, v79
	v_rcp_f32_e32 v76, v76
	v_rcp_f32_e32 v77, v77
	v_rcp_f32_e32 v78, v78
	v_rcp_f32_e32 v79, v79
	v_add_f32_e32 v72, 1.0, v72
	v_add_f32_e32 v73, 1.0, v73
	v_add_f32_e32 v74, 1.0, v74
	v_add_f32_e32 v75, 1.0, v75
	v_add_f32_e32 v64, 1.0, v64
	v_rcp_f32_e32 v72, v72
	v_rcp_f32_e32 v73, v73
	v_rcp_f32_e32 v74, v74
	v_rcp_f32_e32 v75, v75
	v_add_f32_e32 v68, 1.0, v68
	v_add_f32_e32 v69, 1.0, v69
	v_add_f32_e32 v70, 1.0, v70
	v_add_f32_e32 v71, 1.0, v71
	v_rcp_f32_e32 v118, v64
	v_add_f32_e32 v64, 1.0, v65
	v_rcp_f32_e32 v68, v68
	v_rcp_f32_e32 v69, v69
	v_rcp_f32_e32 v70, v70
	v_rcp_f32_e32 v71, v71
	v_rcp_f32_e32 v119, v64
	v_lshlrev_b64 v[64:65], 12, v[114:115]
	v_lshl_add_u64 v[64:65], s[84:85], 0, v[64:65]
	v_lshlrev_b32_e32 v88, 16, v98
	v_and_b32_e32 v89, 0xffff0000, v98
	v_lshlrev_b32_e32 v90, 16, v102
	v_and_b32_e32 v91, 0xffff0000, v102
	v_lshlrev_b32_e32 v92, 16, v99
	v_and_b32_e32 v93, 0xffff0000, v99
	v_lshlrev_b32_e32 v94, 16, v103
	v_and_b32_e32 v95, 0xffff0000, v103
	v_lshl_add_u64 v[114:115], v[64:65], 0, v[112:113]
	v_pk_fma_f32 v[218:219], v[78:79], v[84:85], v[86:87]
	v_pk_fma_f32 v[216:217], v[76:77], v[80:81], v[82:83]
	s_waitcnt vmcnt(0)
	v_lshlrev_b32_e32 v98, 16, v108
	v_and_b32_e32 v99, 0xffff0000, v108
	v_lshlrev_b32_e32 v102, 16, v109
	v_and_b32_e32 v103, 0xffff0000, v109
	v_lshlrev_b32_e32 v108, 16, v106
	v_and_b32_e32 v109, 0xffff0000, v106
	v_pk_fma_f32 v[222:223], v[74:75], v[92:93], v[94:95]
	v_pk_fma_f32 v[220:221], v[72:73], v[88:89], v[90:91]
	v_lshlrev_b32_e32 v116, 16, v110
	v_and_b32_e32 v117, 0xffff0000, v110
	v_lshlrev_b32_e32 v106, 16, v107
	v_and_b32_e32 v107, 0xffff0000, v107
	v_lshlrev_b32_e32 v110, 16, v111
	v_and_b32_e32 v111, 0xffff0000, v111
	s_nop 1
	v_pk_fma_f32 v[226:227], v[70:71], v[100:101], v[102:103]
	v_pk_fma_f32 v[224:225], v[68:69], v[96:97], v[98:99]
	v_add_u32_e32 v96, 0x80, v140
	v_ashrrev_i32_e32 v97, 31, v96
	s_nop 0
	v_pk_fma_f32 v[230:231], v[118:119], v[106:107], v[110:111]
	v_pk_fma_f32 v[228:229], v[104:105], v[108:109], v[116:117]
	s_nop 1
	v_permlane16_swap_b32_e32 v216, v220
	v_permlane16_swap_b32_e32 v217, v221
	v_permlane16_swap_b32_e32 v218, v222
	v_permlane16_swap_b32_e32 v219, v223
	v_permlane16_swap_b32_e32 v224, v228
	v_permlane16_swap_b32_e32 v225, v229
	v_permlane16_swap_b32_e32 v226, v230
	v_permlane16_swap_b32_e32 v227, v231
	v_permlane32_swap_b32_e32 v216, v224
	v_permlane32_swap_b32_e32 v217, v225
	v_permlane32_swap_b32_e32 v218, v226
	v_permlane32_swap_b32_e32 v219, v227
	v_permlane32_swap_b32_e32 v220, v228
	v_permlane32_swap_b32_e32 v221, v229
	v_permlane32_swap_b32_e32 v222, v230
	v_permlane32_swap_b32_e32 v223, v231
	v_lshl_add_u64 v[234:235], v[114:115], 0, v[232:233]
	global_store_dwordx4 v[234:235], v[216:219], off
	global_store_dwordx4 v[234:235], v[220:223], off offset:64
	global_store_dwordx4 v[234:235], v[224:227], off offset:128
	global_store_dwordx4 v[234:235], v[228:231], off offset:192
	s_nop 1
	v_lshlrev_b64 v[64:65], 6, v[96:97]
	v_lshl_add_u64 v[80:81], s[6:7], 0, v[64:65]
	v_lshlrev_b64 v[80:81], 11, v[96:97]
	v_lshl_add_u64 v[82:83], s[8:9], 0, v[80:81]
	v_lshl_add_u64 v[98:99], v[82:83], 0, v[138:139]
	v_lshl_add_u64 v[84:85], s[0:1], 0, v[80:81]
	global_load_dwordx4 v[80:83], v[98:99], off
	v_lshl_add_u64 v[100:101], v[84:85], 0, v[138:139]
	global_load_dwordx4 v[84:87], v[100:101], off
	global_load_dwordx4 v[88:91], v[98:99], off offset:16
	global_load_dwordx4 v[92:95], v[100:101], off offset:16
	s_waitcnt vmcnt(7)
	s_waitcnt vmcnt(6)
	s_waitcnt vmcnt(5)
	s_waitcnt vmcnt(4)
	s_waitcnt vmcnt(3)
	v_lshlrev_b32_e32 v68, 16, v81
	v_and_b32_e32 v69, 0xffff0000, v81
	s_nop 1
	v_mov_b32_e32 v64, v212
	v_fmamk_f32 v64, v64, 0x3a800000, v150
	v_mul_f32_e32 v65, 0x4b800000, v64
	v_cmp_gt_f32_e32 vcc, s51, v64
	s_waitcnt vmcnt(1)
	v_and_b32_e32 v81, 0xffff0000, v88
	v_lshlrev_b32_e32 v66, 16, v84
	v_cndmask_b32_e32 v64, v64, v65, vcc
	v_rsq_f32_e32 v64, v64
	v_and_b32_e32 v67, 0xffff0000, v84
	v_lshlrev_b32_e32 v70, 16, v85
	v_and_b32_e32 v71, 0xffff0000, v85
	v_mul_f32_e32 v65, 0x45800000, v64
	v_cndmask_b32_e32 v64, v64, v65, vcc
	v_mul_f32_e32 v99, 0xbfb8aa3b, v64
	v_mul_f32_e32 v48, v48, v99
	v_exp_f32_e32 v48, v48
	v_mul_f32_e32 v49, v49, v99
	v_exp_f32_e32 v49, v49
	v_mul_f32_e32 v60, v60, v99
	v_add_f32_e32 v48, 1.0, v48
	v_mul_f32_e32 v61, v61, v99
	v_lshlrev_b32_e32 v64, 16, v80
	v_and_b32_e32 v65, 0xffff0000, v80
	v_mul_f32_e32 v62, v62, v99
	v_mul_f32_e32 v63, v63, v99
	v_lshlrev_b32_e32 v80, 16, v88
	v_rcp_f32_e32 v88, v48
	v_add_f32_e32 v48, 1.0, v49
	v_exp_f32_e32 v60, v60
	v_exp_f32_e32 v61, v61
	v_exp_f32_e32 v62, v62
	v_exp_f32_e32 v63, v63
	v_mul_f32_e32 v56, v56, v99
	v_mul_f32_e32 v57, v57, v99
	v_mul_f32_e32 v58, v58, v99
	v_mul_f32_e32 v59, v59, v99
	v_lshlrev_b32_e32 v84, 16, v89
	v_and_b32_e32 v85, 0xffff0000, v89
	v_rcp_f32_e32 v89, v48
	v_mul_f32_e32 v48, v50, v99
	v_exp_f32_e32 v56, v56
	v_exp_f32_e32 v57, v57
	v_exp_f32_e32 v58, v58
	v_exp_f32_e32 v59, v59
	v_mul_f32_e32 v52, v52, v99
	v_mul_f32_e32 v53, v53, v99
	v_mul_f32_e32 v54, v54, v99
	v_mul_f32_e32 v55, v55, v99
	v_exp_f32_e32 v48, v48
	v_mul_f32_e32 v49, v51, v99
	v_exp_f32_e32 v52, v52
	v_exp_f32_e32 v53, v53
	v_exp_f32_e32 v54, v54
	v_exp_f32_e32 v55, v55
	v_exp_f32_e32 v49, v49
	v_add_f32_e32 v60, 1.0, v60
	v_add_f32_e32 v61, 1.0, v61
	v_add_f32_e32 v62, 1.0, v62
	v_add_f32_e32 v63, 1.0, v63
	v_rcp_f32_e32 v60, v60
	v_rcp_f32_e32 v61, v61
	v_rcp_f32_e32 v62, v62
	v_rcp_f32_e32 v63, v63
	v_add_f32_e32 v56, 1.0, v56
	v_add_f32_e32 v57, 1.0, v57
	v_add_f32_e32 v58, 1.0, v58
	v_add_f32_e32 v59, 1.0, v59
	v_add_f32_e32 v48, 1.0, v48
	v_rcp_f32_e32 v56, v56
	v_rcp_f32_e32 v57, v57
	v_rcp_f32_e32 v58, v58
	v_rcp_f32_e32 v59, v59
	v_add_f32_e32 v52, 1.0, v52
	v_add_f32_e32 v53, 1.0, v53
	v_add_f32_e32 v54, 1.0, v54
	v_add_f32_e32 v55, 1.0, v55
	v_rcp_f32_e32 v100, v48
	v_add_f32_e32 v48, 1.0, v49
	v_rcp_f32_e32 v52, v52
	v_rcp_f32_e32 v53, v53
	v_rcp_f32_e32 v54, v54
	v_rcp_f32_e32 v55, v55
	v_rcp_f32_e32 v101, v48
	v_lshlrev_b64 v[48:49], 12, v[96:97]
	v_lshl_add_u64 v[48:49], s[84:85], 0, v[48:49]
	v_lshlrev_b32_e32 v72, 16, v82
	v_and_b32_e32 v73, 0xffff0000, v82
	v_lshlrev_b32_e32 v74, 16, v86
	v_and_b32_e32 v75, 0xffff0000, v86
	v_lshlrev_b32_e32 v76, 16, v83
	v_and_b32_e32 v77, 0xffff0000, v83
	v_lshlrev_b32_e32 v78, 16, v87
	v_and_b32_e32 v79, 0xffff0000, v87
	v_lshl_add_u64 v[96:97], v[48:49], 0, v[112:113]
	v_pk_fma_f32 v[218:219], v[62:63], v[68:69], v[70:71]
	v_pk_fma_f32 v[216:217], v[60:61], v[64:65], v[66:67]
	s_waitcnt vmcnt(0)
	v_lshlrev_b32_e32 v82, 16, v92
	v_and_b32_e32 v83, 0xffff0000, v92
	v_lshlrev_b32_e32 v86, 16, v93
	v_and_b32_e32 v87, 0xffff0000, v93
	v_lshlrev_b32_e32 v92, 16, v90
	v_and_b32_e32 v93, 0xffff0000, v90
	v_pk_fma_f32 v[222:223], v[58:59], v[76:77], v[78:79]
	v_pk_fma_f32 v[220:221], v[56:57], v[72:73], v[74:75]
	v_lshlrev_b32_e32 v98, 16, v94
	v_and_b32_e32 v99, 0xffff0000, v94
	v_lshlrev_b32_e32 v90, 16, v91
	v_and_b32_e32 v91, 0xffff0000, v91
	v_lshlrev_b32_e32 v94, 16, v95
	v_and_b32_e32 v95, 0xffff0000, v95
	s_nop 1
	v_pk_fma_f32 v[226:227], v[54:55], v[84:85], v[86:87]
	v_pk_fma_f32 v[224:225], v[52:53], v[80:81], v[82:83]
	v_add_u32_e32 v80, 0x90, v140
	v_ashrrev_i32_e32 v81, 31, v80
	s_nop 0
	v_pk_fma_f32 v[230:231], v[100:101], v[90:91], v[94:95]
	v_pk_fma_f32 v[228:229], v[88:89], v[92:93], v[98:99]
	s_nop 1
	v_permlane16_swap_b32_e32 v216, v220
	v_permlane16_swap_b32_e32 v217, v221
	v_permlane16_swap_b32_e32 v218, v222
	v_permlane16_swap_b32_e32 v219, v223
	v_permlane16_swap_b32_e32 v224, v228
	v_permlane16_swap_b32_e32 v225, v229
	v_permlane16_swap_b32_e32 v226, v230
	v_permlane16_swap_b32_e32 v227, v231
	v_permlane32_swap_b32_e32 v216, v224
	v_permlane32_swap_b32_e32 v217, v225
	v_permlane32_swap_b32_e32 v218, v226
	v_permlane32_swap_b32_e32 v219, v227
	v_permlane32_swap_b32_e32 v220, v228
	v_permlane32_swap_b32_e32 v221, v229
	v_permlane32_swap_b32_e32 v222, v230
	v_permlane32_swap_b32_e32 v223, v231
	v_lshl_add_u64 v[234:235], v[96:97], 0, v[232:233]
	global_store_dwordx4 v[234:235], v[216:219], off
	global_store_dwordx4 v[234:235], v[220:223], off offset:64
	global_store_dwordx4 v[234:235], v[224:227], off offset:128
	global_store_dwordx4 v[234:235], v[228:231], off offset:192
	s_nop 1
	v_lshlrev_b64 v[48:49], 6, v[80:81]
	v_lshl_add_u64 v[64:65], s[6:7], 0, v[48:49]
	v_lshlrev_b64 v[64:65], 11, v[80:81]
	v_lshl_add_u64 v[66:67], s[8:9], 0, v[64:65]
	v_lshl_add_u64 v[82:83], v[66:67], 0, v[138:139]
	v_lshl_add_u64 v[68:69], s[0:1], 0, v[64:65]
	global_load_dwordx4 v[64:67], v[82:83], off
	v_lshl_add_u64 v[84:85], v[68:69], 0, v[138:139]
	global_load_dwordx4 v[68:71], v[84:85], off
	global_load_dwordx4 v[72:75], v[82:83], off offset:16
	global_load_dwordx4 v[76:79], v[84:85], off offset:16
	s_waitcnt vmcnt(7)
	s_waitcnt vmcnt(6)
	s_waitcnt vmcnt(5)
	s_waitcnt vmcnt(4)
	s_waitcnt vmcnt(3)
	v_lshlrev_b32_e32 v52, 16, v65
	v_and_b32_e32 v53, 0xffff0000, v65
	s_nop 1
	v_mov_b32_e32 v48, v213
	v_fmamk_f32 v48, v48, 0x3a800000, v150
	v_mul_f32_e32 v49, 0x4b800000, v48
	v_cmp_gt_f32_e32 vcc, s51, v48
	s_waitcnt vmcnt(1)
	v_and_b32_e32 v65, 0xffff0000, v72
	v_lshlrev_b32_e32 v50, 16, v68
	v_cndmask_b32_e32 v48, v48, v49, vcc
	v_rsq_f32_e32 v48, v48
	v_and_b32_e32 v51, 0xffff0000, v68
	v_lshlrev_b32_e32 v54, 16, v69
	v_and_b32_e32 v55, 0xffff0000, v69
	v_mul_f32_e32 v49, 0x45800000, v48
	v_cndmask_b32_e32 v48, v48, v49, vcc
	v_mul_f32_e32 v83, 0xbfb8aa3b, v48
	v_mul_f32_e32 v32, v32, v83
	v_exp_f32_e32 v32, v32
	v_mul_f32_e32 v33, v33, v83
	v_exp_f32_e32 v33, v33
	v_mul_f32_e32 v44, v44, v83
	v_add_f32_e32 v32, 1.0, v32
	v_mul_f32_e32 v45, v45, v83
	v_lshlrev_b32_e32 v48, 16, v64
	v_and_b32_e32 v49, 0xffff0000, v64
	v_mul_f32_e32 v46, v46, v83
	v_mul_f32_e32 v47, v47, v83
	v_lshlrev_b32_e32 v64, 16, v72
	v_rcp_f32_e32 v72, v32
	v_add_f32_e32 v32, 1.0, v33
	v_exp_f32_e32 v44, v44
	v_exp_f32_e32 v45, v45
	v_exp_f32_e32 v46, v46
	v_exp_f32_e32 v47, v47
	v_mul_f32_e32 v40, v40, v83
	v_mul_f32_e32 v41, v41, v83
	v_mul_f32_e32 v42, v42, v83
	v_mul_f32_e32 v43, v43, v83
	v_lshlrev_b32_e32 v68, 16, v73
	v_and_b32_e32 v69, 0xffff0000, v73
	v_rcp_f32_e32 v73, v32
	v_mul_f32_e32 v32, v34, v83
	v_exp_f32_e32 v40, v40
	v_exp_f32_e32 v41, v41
	v_exp_f32_e32 v42, v42
	v_exp_f32_e32 v43, v43
	v_mul_f32_e32 v36, v36, v83
	v_mul_f32_e32 v37, v37, v83
	v_mul_f32_e32 v38, v38, v83
	v_mul_f32_e32 v39, v39, v83
	v_exp_f32_e32 v32, v32
	v_mul_f32_e32 v33, v35, v83
	v_exp_f32_e32 v36, v36
	v_exp_f32_e32 v37, v37
	v_exp_f32_e32 v38, v38
	v_exp_f32_e32 v39, v39
	v_exp_f32_e32 v33, v33
	v_add_f32_e32 v44, 1.0, v44
	v_add_f32_e32 v45, 1.0, v45
	v_add_f32_e32 v46, 1.0, v46
	v_add_f32_e32 v47, 1.0, v47
	v_rcp_f32_e32 v44, v44
	v_rcp_f32_e32 v45, v45
	v_rcp_f32_e32 v46, v46
	v_rcp_f32_e32 v47, v47
	v_add_f32_e32 v40, 1.0, v40
	v_add_f32_e32 v41, 1.0, v41
	v_add_f32_e32 v42, 1.0, v42
	v_add_f32_e32 v43, 1.0, v43
	v_add_f32_e32 v32, 1.0, v32
	v_rcp_f32_e32 v40, v40
	v_rcp_f32_e32 v41, v41
	v_rcp_f32_e32 v42, v42
	v_rcp_f32_e32 v43, v43
	v_add_f32_e32 v36, 1.0, v36
	v_add_f32_e32 v37, 1.0, v37
	v_add_f32_e32 v38, 1.0, v38
	v_add_f32_e32 v39, 1.0, v39
	v_rcp_f32_e32 v84, v32
	v_add_f32_e32 v32, 1.0, v33
	v_rcp_f32_e32 v36, v36
	v_rcp_f32_e32 v37, v37
	v_rcp_f32_e32 v38, v38
	v_rcp_f32_e32 v39, v39
	v_rcp_f32_e32 v85, v32
	v_lshlrev_b64 v[32:33], 12, v[80:81]
	v_lshl_add_u64 v[32:33], s[84:85], 0, v[32:33]
	v_lshlrev_b32_e32 v56, 16, v66
	v_and_b32_e32 v57, 0xffff0000, v66
	v_lshlrev_b32_e32 v58, 16, v70
	v_and_b32_e32 v59, 0xffff0000, v70
	v_lshlrev_b32_e32 v60, 16, v67
	v_and_b32_e32 v61, 0xffff0000, v67
	v_lshlrev_b32_e32 v62, 16, v71
	v_and_b32_e32 v63, 0xffff0000, v71
	v_lshl_add_u64 v[80:81], v[32:33], 0, v[112:113]
	v_pk_fma_f32 v[218:219], v[46:47], v[52:53], v[54:55]
	v_pk_fma_f32 v[216:217], v[44:45], v[48:49], v[50:51]
	s_waitcnt vmcnt(0)
	v_lshlrev_b32_e32 v66, 16, v76
	v_and_b32_e32 v67, 0xffff0000, v76
	v_lshlrev_b32_e32 v70, 16, v77
	v_and_b32_e32 v71, 0xffff0000, v77
	v_lshlrev_b32_e32 v76, 16, v74
	v_and_b32_e32 v77, 0xffff0000, v74
	v_pk_fma_f32 v[222:223], v[42:43], v[60:61], v[62:63]
	v_pk_fma_f32 v[220:221], v[40:41], v[56:57], v[58:59]
	v_lshlrev_b32_e32 v82, 16, v78
	v_and_b32_e32 v83, 0xffff0000, v78
	v_lshlrev_b32_e32 v74, 16, v75
	v_and_b32_e32 v75, 0xffff0000, v75
	v_lshlrev_b32_e32 v78, 16, v79
	v_and_b32_e32 v79, 0xffff0000, v79
	s_nop 1
	v_pk_fma_f32 v[226:227], v[38:39], v[68:69], v[70:71]
	v_pk_fma_f32 v[224:225], v[36:37], v[64:65], v[66:67]
	v_add_u32_e32 v64, 0xa0, v140
	v_ashrrev_i32_e32 v65, 31, v64
	s_nop 0
	v_pk_fma_f32 v[230:231], v[84:85], v[74:75], v[78:79]
	v_pk_fma_f32 v[228:229], v[72:73], v[76:77], v[82:83]
	s_nop 1
	v_permlane16_swap_b32_e32 v216, v220
	v_permlane16_swap_b32_e32 v217, v221
	v_permlane16_swap_b32_e32 v218, v222
	v_permlane16_swap_b32_e32 v219, v223
	v_permlane16_swap_b32_e32 v224, v228
	v_permlane16_swap_b32_e32 v225, v229
	v_permlane16_swap_b32_e32 v226, v230
	v_permlane16_swap_b32_e32 v227, v231
	v_permlane32_swap_b32_e32 v216, v224
	v_permlane32_swap_b32_e32 v217, v225
	v_permlane32_swap_b32_e32 v218, v226
	v_permlane32_swap_b32_e32 v219, v227
	v_permlane32_swap_b32_e32 v220, v228
	v_permlane32_swap_b32_e32 v221, v229
	v_permlane32_swap_b32_e32 v222, v230
	v_permlane32_swap_b32_e32 v223, v231
	v_lshl_add_u64 v[234:235], v[80:81], 0, v[232:233]
	global_store_dwordx4 v[234:235], v[216:219], off
	global_store_dwordx4 v[234:235], v[220:223], off offset:64
	global_store_dwordx4 v[234:235], v[224:227], off offset:128
	global_store_dwordx4 v[234:235], v[228:231], off offset:192
	s_nop 1
	v_lshlrev_b64 v[32:33], 6, v[64:65]
	v_lshl_add_u64 v[48:49], s[6:7], 0, v[32:33]
	v_lshlrev_b64 v[48:49], 11, v[64:65]
	v_lshl_add_u64 v[50:51], s[8:9], 0, v[48:49]
	v_lshl_add_u64 v[66:67], v[50:51], 0, v[138:139]
	v_lshl_add_u64 v[52:53], s[0:1], 0, v[48:49]
	global_load_dwordx4 v[48:51], v[66:67], off
	v_lshl_add_u64 v[68:69], v[52:53], 0, v[138:139]
	global_load_dwordx4 v[52:55], v[68:69], off
	global_load_dwordx4 v[56:59], v[66:67], off offset:16
	global_load_dwordx4 v[60:63], v[68:69], off offset:16
	s_waitcnt vmcnt(7)
	s_waitcnt vmcnt(6)
	s_waitcnt vmcnt(5)
	s_waitcnt vmcnt(4)
	s_waitcnt vmcnt(3)
	v_lshlrev_b32_e32 v36, 16, v49
	v_and_b32_e32 v37, 0xffff0000, v49
	s_nop 1
	v_mov_b32_e32 v32, v214
	v_fmamk_f32 v32, v32, 0x3a800000, v150
	v_mul_f32_e32 v33, 0x4b800000, v32
	v_cmp_gt_f32_e32 vcc, s51, v32
	s_waitcnt vmcnt(1)
	v_and_b32_e32 v49, 0xffff0000, v56
	v_lshlrev_b32_e32 v34, 16, v52
	v_cndmask_b32_e32 v32, v32, v33, vcc
	v_rsq_f32_e32 v32, v32
	v_and_b32_e32 v35, 0xffff0000, v52
	v_lshlrev_b32_e32 v38, 16, v53
	v_and_b32_e32 v39, 0xffff0000, v53
	v_mul_f32_e32 v33, 0x45800000, v32
	v_cndmask_b32_e32 v32, v32, v33, vcc
	v_mul_f32_e32 v67, 0xbfb8aa3b, v32
	v_mul_f32_e32 v16, v16, v67
	v_exp_f32_e32 v16, v16
	v_mul_f32_e32 v17, v17, v67
	v_exp_f32_e32 v17, v17
	v_mul_f32_e32 v28, v28, v67
	v_add_f32_e32 v16, 1.0, v16
	v_mul_f32_e32 v29, v29, v67
	v_lshlrev_b32_e32 v32, 16, v48
	v_and_b32_e32 v33, 0xffff0000, v48
	v_mul_f32_e32 v30, v30, v67
	v_mul_f32_e32 v31, v31, v67
	v_lshlrev_b32_e32 v48, 16, v56
	v_rcp_f32_e32 v56, v16
	v_add_f32_e32 v16, 1.0, v17
	v_exp_f32_e32 v28, v28
	v_exp_f32_e32 v29, v29
	v_exp_f32_e32 v30, v30
	v_exp_f32_e32 v31, v31
	v_mul_f32_e32 v24, v24, v67
	v_mul_f32_e32 v25, v25, v67
	v_mul_f32_e32 v26, v26, v67
	v_mul_f32_e32 v27, v27, v67
	v_lshlrev_b32_e32 v52, 16, v57
	v_and_b32_e32 v53, 0xffff0000, v57
	v_rcp_f32_e32 v57, v16
	v_mul_f32_e32 v16, v18, v67
	v_exp_f32_e32 v24, v24
	v_exp_f32_e32 v25, v25
	v_exp_f32_e32 v26, v26
	v_exp_f32_e32 v27, v27
	v_mul_f32_e32 v20, v20, v67
	v_mul_f32_e32 v21, v21, v67
	v_mul_f32_e32 v22, v22, v67
	v_mul_f32_e32 v23, v23, v67
	v_exp_f32_e32 v16, v16
	v_mul_f32_e32 v17, v19, v67
	v_exp_f32_e32 v20, v20
	v_exp_f32_e32 v21, v21
	v_exp_f32_e32 v22, v22
	v_exp_f32_e32 v23, v23
	v_exp_f32_e32 v17, v17
	v_add_f32_e32 v28, 1.0, v28
	v_add_f32_e32 v29, 1.0, v29
	v_add_f32_e32 v30, 1.0, v30
	v_add_f32_e32 v31, 1.0, v31
	v_rcp_f32_e32 v28, v28
	v_rcp_f32_e32 v29, v29
	v_rcp_f32_e32 v30, v30
	v_rcp_f32_e32 v31, v31
	v_add_f32_e32 v24, 1.0, v24
	v_add_f32_e32 v25, 1.0, v25
	v_add_f32_e32 v26, 1.0, v26
	v_add_f32_e32 v27, 1.0, v27
	v_add_f32_e32 v16, 1.0, v16
	v_rcp_f32_e32 v24, v24
	v_rcp_f32_e32 v25, v25
	v_rcp_f32_e32 v26, v26
	v_rcp_f32_e32 v27, v27
	v_add_f32_e32 v20, 1.0, v20
	v_add_f32_e32 v21, 1.0, v21
	v_add_f32_e32 v22, 1.0, v22
	v_add_f32_e32 v23, 1.0, v23
	v_rcp_f32_e32 v68, v16
	v_add_f32_e32 v16, 1.0, v17
	v_rcp_f32_e32 v20, v20
	v_rcp_f32_e32 v21, v21
	v_rcp_f32_e32 v22, v22
	v_rcp_f32_e32 v23, v23
	v_rcp_f32_e32 v69, v16
	v_lshlrev_b64 v[16:17], 12, v[64:65]
	v_lshl_add_u64 v[16:17], s[84:85], 0, v[16:17]
	v_lshlrev_b32_e32 v40, 16, v50
	v_and_b32_e32 v41, 0xffff0000, v50
	v_lshlrev_b32_e32 v42, 16, v54
	v_and_b32_e32 v43, 0xffff0000, v54
	v_lshlrev_b32_e32 v44, 16, v51
	v_and_b32_e32 v45, 0xffff0000, v51
	v_lshlrev_b32_e32 v46, 16, v55
	v_and_b32_e32 v47, 0xffff0000, v55
	v_lshl_add_u64 v[64:65], v[16:17], 0, v[112:113]
	v_pk_fma_f32 v[218:219], v[30:31], v[36:37], v[38:39]
	v_pk_fma_f32 v[216:217], v[28:29], v[32:33], v[34:35]
	s_waitcnt vmcnt(0)
	v_lshlrev_b32_e32 v50, 16, v60
	v_and_b32_e32 v51, 0xffff0000, v60
	v_lshlrev_b32_e32 v54, 16, v61
	v_and_b32_e32 v55, 0xffff0000, v61
	v_lshlrev_b32_e32 v60, 16, v58
	v_and_b32_e32 v61, 0xffff0000, v58
	v_pk_fma_f32 v[222:223], v[26:27], v[44:45], v[46:47]
	v_pk_fma_f32 v[220:221], v[24:25], v[40:41], v[42:43]
	v_lshlrev_b32_e32 v66, 16, v62
	v_and_b32_e32 v67, 0xffff0000, v62
	v_lshlrev_b32_e32 v58, 16, v59
	v_and_b32_e32 v59, 0xffff0000, v59
	v_lshlrev_b32_e32 v62, 16, v63
	v_and_b32_e32 v63, 0xffff0000, v63
	s_nop 1
	v_pk_fma_f32 v[226:227], v[22:23], v[52:53], v[54:55]
	v_pk_fma_f32 v[224:225], v[20:21], v[48:49], v[50:51]
	v_add_u32_e32 v48, 0xb0, v140
	v_ashrrev_i32_e32 v49, 31, v48
	s_nop 0
	v_pk_fma_f32 v[230:231], v[68:69], v[58:59], v[62:63]
	v_pk_fma_f32 v[228:229], v[56:57], v[60:61], v[66:67]
	s_nop 1
	v_permlane16_swap_b32_e32 v216, v220
	v_permlane16_swap_b32_e32 v217, v221
	v_permlane16_swap_b32_e32 v218, v222
	v_permlane16_swap_b32_e32 v219, v223
	v_permlane16_swap_b32_e32 v224, v228
	v_permlane16_swap_b32_e32 v225, v229
	v_permlane16_swap_b32_e32 v226, v230
	v_permlane16_swap_b32_e32 v227, v231
	v_permlane32_swap_b32_e32 v216, v224
	v_permlane32_swap_b32_e32 v217, v225
	v_permlane32_swap_b32_e32 v218, v226
	v_permlane32_swap_b32_e32 v219, v227
	v_permlane32_swap_b32_e32 v220, v228
	v_permlane32_swap_b32_e32 v221, v229
	v_permlane32_swap_b32_e32 v222, v230
	v_permlane32_swap_b32_e32 v223, v231
	v_lshl_add_u64 v[234:235], v[64:65], 0, v[232:233]
	global_store_dwordx4 v[234:235], v[216:219], off
	global_store_dwordx4 v[234:235], v[220:223], off offset:64
	global_store_dwordx4 v[234:235], v[224:227], off offset:128
	global_store_dwordx4 v[234:235], v[228:231], off offset:192
	s_nop 1
	v_lshlrev_b64 v[16:17], 6, v[48:49]
	v_lshl_add_u64 v[32:33], s[6:7], 0, v[16:17]
	v_lshlrev_b64 v[32:33], 11, v[48:49]
	v_lshl_add_u64 v[34:35], s[8:9], 0, v[32:33]
	v_lshl_add_u64 v[50:51], v[34:35], 0, v[138:139]
	v_lshl_add_u64 v[36:37], s[0:1], 0, v[32:33]
	global_load_dwordx4 v[32:35], v[50:51], off
	v_lshl_add_u64 v[52:53], v[36:37], 0, v[138:139]
	global_load_dwordx4 v[36:39], v[52:53], off
	global_load_dwordx4 v[40:43], v[50:51], off offset:16
	global_load_dwordx4 v[44:47], v[52:53], off offset:16
	s_waitcnt vmcnt(7)
	s_waitcnt vmcnt(6)
	s_waitcnt vmcnt(5)
	s_waitcnt vmcnt(4)
	s_waitcnt vmcnt(3)
	v_lshlrev_b32_e32 v20, 16, v33
	v_and_b32_e32 v21, 0xffff0000, v33
	s_nop 1
	v_mov_b32_e32 v16, v215
	v_fmamk_f32 v16, v16, 0x3a800000, v150
	v_mul_f32_e32 v17, 0x4b800000, v16
	v_cmp_gt_f32_e32 vcc, s51, v16
	s_waitcnt vmcnt(1)
	v_and_b32_e32 v33, 0xffff0000, v40
	v_lshlrev_b32_e32 v18, 16, v36
	v_cndmask_b32_e32 v16, v16, v17, vcc
	v_rsq_f32_e32 v16, v16
	v_and_b32_e32 v19, 0xffff0000, v36
	v_lshlrev_b32_e32 v22, 16, v37
	v_and_b32_e32 v23, 0xffff0000, v37
	v_mul_f32_e32 v17, 0x45800000, v16
	v_cndmask_b32_e32 v16, v16, v17, vcc
	v_mul_f32_e32 v51, 0xbfb8aa3b, v16
	v_mul_f32_e32 v0, v0, v51
	v_exp_f32_e32 v0, v0
	v_mul_f32_e32 v1, v1, v51
	v_exp_f32_e32 v1, v1
	v_mul_f32_e32 v12, v12, v51
	v_add_f32_e32 v0, 1.0, v0
	v_mul_f32_e32 v13, v13, v51
	v_lshlrev_b32_e32 v16, 16, v32
	v_and_b32_e32 v17, 0xffff0000, v32
	v_mul_f32_e32 v14, v14, v51
	v_mul_f32_e32 v15, v15, v51
	v_lshlrev_b32_e32 v32, 16, v40
	v_rcp_f32_e32 v40, v0
	v_add_f32_e32 v0, 1.0, v1
	v_exp_f32_e32 v12, v12
	v_exp_f32_e32 v13, v13
	v_exp_f32_e32 v14, v14
	v_exp_f32_e32 v15, v15
	v_mul_f32_e32 v8, v8, v51
	v_mul_f32_e32 v9, v9, v51
	v_mul_f32_e32 v10, v10, v51
	v_mul_f32_e32 v11, v11, v51
	v_lshlrev_b32_e32 v36, 16, v41
	v_and_b32_e32 v37, 0xffff0000, v41
	v_rcp_f32_e32 v41, v0
	v_mul_f32_e32 v0, v2, v51
	v_exp_f32_e32 v8, v8
	v_exp_f32_e32 v9, v9
	v_exp_f32_e32 v10, v10
	v_exp_f32_e32 v11, v11
	v_mul_f32_e32 v4, v4, v51
	v_mul_f32_e32 v5, v5, v51
	v_mul_f32_e32 v6, v6, v51
	v_mul_f32_e32 v7, v7, v51
	v_exp_f32_e32 v0, v0
	v_mul_f32_e32 v1, v3, v51
	v_exp_f32_e32 v4, v4
	v_exp_f32_e32 v5, v5
	v_exp_f32_e32 v6, v6
	v_exp_f32_e32 v7, v7
	v_exp_f32_e32 v1, v1
	v_add_f32_e32 v12, 1.0, v12
	v_add_f32_e32 v13, 1.0, v13
	v_add_f32_e32 v14, 1.0, v14
	v_add_f32_e32 v15, 1.0, v15
	v_rcp_f32_e32 v12, v12
	v_rcp_f32_e32 v13, v13
	v_rcp_f32_e32 v14, v14
	v_rcp_f32_e32 v15, v15
	v_add_f32_e32 v8, 1.0, v8
	v_add_f32_e32 v9, 1.0, v9
	v_add_f32_e32 v10, 1.0, v10
	v_add_f32_e32 v11, 1.0, v11
	v_add_f32_e32 v0, 1.0, v0
	v_rcp_f32_e32 v8, v8
	v_rcp_f32_e32 v9, v9
	v_rcp_f32_e32 v10, v10
	v_rcp_f32_e32 v11, v11
	v_add_f32_e32 v4, 1.0, v4
	v_add_f32_e32 v5, 1.0, v5
	v_add_f32_e32 v6, 1.0, v6
	v_add_f32_e32 v7, 1.0, v7
	v_rcp_f32_e32 v52, v0
	v_add_f32_e32 v0, 1.0, v1
	v_rcp_f32_e32 v4, v4
	v_rcp_f32_e32 v5, v5
	v_rcp_f32_e32 v6, v6
	v_rcp_f32_e32 v7, v7
	v_rcp_f32_e32 v53, v0
	v_lshlrev_b64 v[0:1], 12, v[48:49]
	v_lshl_add_u64 v[0:1], s[84:85], 0, v[0:1]
	v_lshlrev_b32_e32 v24, 16, v34
	v_and_b32_e32 v25, 0xffff0000, v34
	v_lshlrev_b32_e32 v26, 16, v38
	v_and_b32_e32 v27, 0xffff0000, v38
	v_lshlrev_b32_e32 v28, 16, v35
	v_and_b32_e32 v29, 0xffff0000, v35
	v_lshlrev_b32_e32 v30, 16, v39
	v_and_b32_e32 v31, 0xffff0000, v39
	v_lshl_add_u64 v[48:49], v[0:1], 0, v[112:113]
	v_pk_fma_f32 v[218:219], v[14:15], v[20:21], v[22:23]
	v_pk_fma_f32 v[216:217], v[12:13], v[16:17], v[18:19]
	s_waitcnt vmcnt(0)
	v_lshlrev_b32_e32 v34, 16, v44
	v_and_b32_e32 v35, 0xffff0000, v44
	v_lshlrev_b32_e32 v38, 16, v45
	v_and_b32_e32 v39, 0xffff0000, v45
	v_lshlrev_b32_e32 v44, 16, v42
	v_and_b32_e32 v45, 0xffff0000, v42
	v_pk_fma_f32 v[222:223], v[10:11], v[28:29], v[30:31]
	v_pk_fma_f32 v[220:221], v[8:9], v[24:25], v[26:27]
	v_lshlrev_b32_e32 v50, 16, v46
	v_and_b32_e32 v51, 0xffff0000, v46
	v_lshlrev_b32_e32 v42, 16, v43
	v_and_b32_e32 v43, 0xffff0000, v43
	v_lshlrev_b32_e32 v46, 16, v47
	v_and_b32_e32 v47, 0xffff0000, v47
	s_nop 1
	v_pk_fma_f32 v[226:227], v[6:7], v[36:37], v[38:39]
	v_pk_fma_f32 v[224:225], v[4:5], v[32:33], v[34:35]
	s_nop 1
	v_pk_fma_f32 v[230:231], v[52:53], v[42:43], v[46:47]
	v_pk_fma_f32 v[228:229], v[40:41], v[44:45], v[50:51]
	s_nop 1
	v_permlane16_swap_b32_e32 v216, v220
	v_permlane16_swap_b32_e32 v217, v221
	v_permlane16_swap_b32_e32 v218, v222
	v_permlane16_swap_b32_e32 v219, v223
	v_permlane16_swap_b32_e32 v224, v228
	v_permlane16_swap_b32_e32 v225, v229
	v_permlane16_swap_b32_e32 v226, v230
	v_permlane16_swap_b32_e32 v227, v231
	v_permlane32_swap_b32_e32 v216, v224
	v_permlane32_swap_b32_e32 v217, v225
	v_permlane32_swap_b32_e32 v218, v226
	v_permlane32_swap_b32_e32 v219, v227
	v_permlane32_swap_b32_e32 v220, v228
	v_permlane32_swap_b32_e32 v221, v229
	v_permlane32_swap_b32_e32 v222, v230
	v_permlane32_swap_b32_e32 v223, v231
	v_lshl_add_u64 v[234:235], v[48:49], 0, v[232:233]
	global_store_dwordx4 v[234:235], v[216:219], off
	global_store_dwordx4 v[234:235], v[220:223], off offset:64
	global_store_dwordx4 v[234:235], v[224:227], off offset:128
	global_store_dwordx4 v[234:235], v[228:231], off offset:192
	s_cbranch_scc1 .LBB0_1643
	s_andn2_b64 vcc, exec, s[4:5]
	s_cbranch_vccnz .LBB0_1642
	s_barrier
	s_branch .LBB0_1642
